# attention row sums with v_pk_add_f32 (33 instead of 66 VALU ops per step), otherwise the best version
# baseline (speedup 1.0000x reference)
.LBB0_679:
	s_cmp_ge_u32 s75, s72
	s_cbranch_scc1 .Lattn_pv_nodma
	v_lshl_add_u32 v227, s36, 15, v230
	s_mov_b32 s37, m0
	s_xor_b32 s6, s36, 1
	s_lshl_b32 s7, s6, 14
	s_add_i32 s7, s7, s69
	s_lshl_b32 s6, s6, 15
	s_add_i32 s6, s6, s70
	ds_read_b64_tr_b16 v[114:115], v227 offset:32768
	ds_read_b64_tr_b16 v[116:117], v227 offset:33280
	ds_read_b64_tr_b16 v[118:119], v227 offset:33792
	ds_read_b64_tr_b16 v[120:121], v227 offset:34304
	ds_read_b64_tr_b16 v[122:123], v227 offset:34816
	ds_read_b64_tr_b16 v[124:125], v227 offset:35328
	ds_read_b64_tr_b16 v[126:127], v227 offset:35840
	ds_read_b64_tr_b16 v[128:129], v227 offset:36352
	ds_read_b64_tr_b16 v[130:131], v227 offset:36864
	ds_read_b64_tr_b16 v[132:133], v227 offset:37376
	ds_read_b64_tr_b16 v[134:135], v227 offset:37888
	ds_read_b64_tr_b16 v[136:137], v227 offset:38400
	v_exp_f32_e32 v146, v146
	v_exp_f32_e32 v147, v147
	v_exp_f32_e32 v162, v162
	v_exp_f32_e32 v163, v163
	v_exp_f32_e32 v148, v148
	v_exp_f32_e32 v149, v149
	v_exp_f32_e32 v164, v164
	v_exp_f32_e32 v165, v165
	v_cvt_pk_bf16_f32 v82, v146, v147
	v_cvt_pk_bf16_f32 v90, v162, v163
	v_exp_f32_e32 v150, v150
	v_exp_f32_e32 v151, v151
	v_exp_f32_e32 v166, v166
	v_exp_f32_e32 v167, v167
	v_cvt_pk_bf16_f32 v83, v148, v149
	v_cvt_pk_bf16_f32 v91, v164, v165
	v_exp_f32_e32 v152, v152
	v_exp_f32_e32 v153, v153
	v_exp_f32_e32 v168, v168
	v_exp_f32_e32 v169, v169
	v_cvt_pk_bf16_f32 v84, v150, v151
	v_cvt_pk_bf16_f32 v92, v166, v167
	v_exp_f32_e32 v154, v154
	v_exp_f32_e32 v155, v155
	v_exp_f32_e32 v170, v170
	v_exp_f32_e32 v171, v171
	v_cvt_pk_bf16_f32 v85, v152, v153
	v_cvt_pk_bf16_f32 v93, v168, v169
	v_exp_f32_e32 v156, v156
	v_exp_f32_e32 v157, v157
	v_exp_f32_e32 v172, v172
	v_exp_f32_e32 v173, v173
	v_cvt_pk_bf16_f32 v86, v154, v155
	v_cvt_pk_bf16_f32 v94, v170, v171
	v_exp_f32_e32 v158, v158
	v_exp_f32_e32 v159, v159
	v_exp_f32_e32 v174, v174
	v_exp_f32_e32 v175, v175
	v_cvt_pk_bf16_f32 v87, v156, v157
	v_cvt_pk_bf16_f32 v95, v172, v173
	v_exp_f32_e32 v160, v160
	v_exp_f32_e32 v161, v161
	v_exp_f32_e32 v176, v176
	v_exp_f32_e32 v177, v177
	v_cvt_pk_bf16_f32 v88, v158, v159
	v_cvt_pk_bf16_f32 v96, v174, v175
	s_nop 0
	v_cvt_pk_bf16_f32 v89, v160, v161
	v_cvt_pk_bf16_f32 v97, v176, v177
	s_waitcnt lgkmcnt(10)
	v_mfma_f32_32x32x16_bf16 v[50:65], v[82:85], v[114:117], v[50:65]
	ds_read_b64_tr_b16 v[138:139], v227 offset:38912
	ds_read_b64_tr_b16 v[140:141], v227 offset:39424
	v_exp_f32_e32 v178, v178
	v_exp_f32_e32 v179, v179
	s_waitcnt lgkmcnt(10)
	v_mfma_f32_32x32x16_bf16 v[50:65], v[86:89], v[118:121], v[50:65]
	ds_read_b64_tr_b16 v[142:143], v227 offset:39936
	ds_read_b64_tr_b16 v[144:145], v227 offset:40448
	s_add_u32 s58, s56, 0x60000
	s_addc_u32 s59, s57, 0
	v_lshl_add_u64 v[228:229], v[238:239], 0, s[58:59]
	s_add_i32 m0, s7, 0x2000
	s_nop 0
	global_load_lds_dwordx4 v[228:229], off
	v_exp_f32_e32 v180, v180
	v_exp_f32_e32 v181, v181
	v_cvt_pk_bf16_f32 v98, v178, v179
	s_waitcnt lgkmcnt(10)
	v_mfma_f32_32x32x16_bf16 v[50:65], v[90:93], v[122:125], v[50:65]
	ds_read_b64_tr_b16 v[114:115], v227 offset:40960
	ds_read_b64_tr_b16 v[116:117], v227 offset:41472
	v_exp_f32_e32 v182, v182
	v_exp_f32_e32 v183, v183
	v_cvt_pk_bf16_f32 v99, v180, v181
	s_waitcnt lgkmcnt(10)
	v_mfma_f32_32x32x16_bf16 v[50:65], v[94:97], v[126:129], v[50:65]
	ds_read_b64_tr_b16 v[118:119], v227 offset:41984
	ds_read_b64_tr_b16 v[120:121], v227 offset:42496
	s_add_u32 s58, s56, 0x20060000
	s_addc_u32 s59, s57, 0
	v_lshl_add_u64 v[228:229], v[240:241], 0, s[58:59]
	s_add_i32 m0, s6, 0x4000
	s_nop 0
	global_load_lds_dwordx4 v[228:229], off
	v_exp_f32_e32 v184, v184
	v_exp_f32_e32 v185, v185
	v_cvt_pk_bf16_f32 v100, v182, v183
	s_waitcnt lgkmcnt(10)
	v_mfma_f32_32x32x16_bf16 v[34:49], v[82:85], v[130:133], v[34:49]
	ds_read_b64_tr_b16 v[122:123], v227 offset:43008
	ds_read_b64_tr_b16 v[124:125], v227 offset:43520
	v_exp_f32_e32 v186, v186
	v_exp_f32_e32 v187, v187
	v_cvt_pk_bf16_f32 v101, v184, v185
	s_waitcnt lgkmcnt(10)
	v_mfma_f32_32x32x16_bf16 v[34:49], v[86:89], v[134:137], v[34:49]
	ds_read_b64_tr_b16 v[126:127], v227 offset:44032
	ds_read_b64_tr_b16 v[128:129], v227 offset:44544
	s_add_u32 s58, s56, 0x20060080
	s_addc_u32 s59, s57, 0
	v_lshl_add_u64 v[228:229], v[240:241], 0, s[58:59]
	s_add_i32 m0, s6, 0x6000
	s_nop 0
	global_load_lds_dwordx4 v[228:229], off
	v_exp_f32_e32 v188, v188
	v_exp_f32_e32 v189, v189
	v_cvt_pk_bf16_f32 v102, v186, v187
	s_waitcnt lgkmcnt(10)
	v_mfma_f32_32x32x16_bf16 v[34:49], v[90:93], v[138:141], v[34:49]
	ds_read_b64_tr_b16 v[130:131], v227 offset:45056
	ds_read_b64_tr_b16 v[132:133], v227 offset:45568
	s_mov_b32 m0, s37
	v_exp_f32_e32 v190, v190
	v_exp_f32_e32 v191, v191
	v_cvt_pk_bf16_f32 v103, v188, v189
	s_waitcnt lgkmcnt(10)
	v_mfma_f32_32x32x16_bf16 v[34:49], v[94:97], v[142:145], v[34:49]
	ds_read_b64_tr_b16 v[134:135], v227 offset:46080
	ds_read_b64_tr_b16 v[136:137], v227 offset:46592
	v_exp_f32_e32 v192, v192
	v_exp_f32_e32 v193, v193
	v_cvt_pk_bf16_f32 v104, v190, v191
	s_waitcnt lgkmcnt(10)
	v_mfma_f32_32x32x16_bf16 v[18:33], v[82:85], v[114:117], v[18:33]
	ds_read_b64_tr_b16 v[138:139], v227 offset:47104
	ds_read_b64_tr_b16 v[140:141], v227 offset:47616
	v_exp_f32_e32 v194, v194
	v_exp_f32_e32 v195, v195
	v_cvt_pk_bf16_f32 v105, v192, v193
	s_waitcnt lgkmcnt(10)
	v_mfma_f32_32x32x16_bf16 v[18:33], v[86:89], v[118:121], v[18:33]
	ds_read_b64_tr_b16 v[142:143], v227 offset:48128
	ds_read_b64_tr_b16 v[144:145], v227 offset:48640
	v_exp_f32_e32 v196, v196
	v_exp_f32_e32 v197, v197
	v_cvt_pk_bf16_f32 v106, v194, v195
	s_waitcnt lgkmcnt(10)
	v_mfma_f32_32x32x16_bf16 v[18:33], v[90:93], v[122:125], v[18:33]
	ds_read_b64_tr_b16 v[114:115], v227 offset:49152
	ds_read_b64_tr_b16 v[116:117], v227 offset:49664
	v_exp_f32_e32 v198, v198
	v_exp_f32_e32 v199, v199
	v_cvt_pk_bf16_f32 v107, v196, v197
	s_waitcnt lgkmcnt(10)
	v_mfma_f32_32x32x16_bf16 v[18:33], v[94:97], v[126:129], v[18:33]
	ds_read_b64_tr_b16 v[118:119], v227 offset:50176
	ds_read_b64_tr_b16 v[120:121], v227 offset:50688
	v_exp_f32_e32 v200, v200
	v_exp_f32_e32 v201, v201
	v_cvt_pk_bf16_f32 v108, v198, v199
	s_waitcnt lgkmcnt(10)
	v_mfma_f32_32x32x16_bf16 v[2:17], v[82:85], v[130:133], v[2:17]
	ds_read_b64_tr_b16 v[122:123], v227 offset:51200
	ds_read_b64_tr_b16 v[124:125], v227 offset:51712
	v_exp_f32_e32 v202, v202
	v_exp_f32_e32 v203, v203
	v_cvt_pk_bf16_f32 v109, v200, v201
	s_waitcnt lgkmcnt(10)
	v_mfma_f32_32x32x16_bf16 v[2:17], v[86:89], v[134:137], v[2:17]
	ds_read_b64_tr_b16 v[126:127], v227 offset:52224
	ds_read_b64_tr_b16 v[128:129], v227 offset:52736
	v_exp_f32_e32 v204, v204
	v_exp_f32_e32 v205, v205
	v_cvt_pk_bf16_f32 v110, v202, v203
	s_waitcnt lgkmcnt(10)
	v_mfma_f32_32x32x16_bf16 v[2:17], v[90:93], v[138:141], v[2:17]
	ds_read_b64_tr_b16 v[130:131], v227 offset:53248
	ds_read_b64_tr_b16 v[132:133], v227 offset:53760
	v_exp_f32_e32 v206, v206
	v_exp_f32_e32 v207, v207
	v_cvt_pk_bf16_f32 v111, v204, v205
	s_waitcnt lgkmcnt(10)
	v_mfma_f32_32x32x16_bf16 v[2:17], v[94:97], v[142:145], v[2:17]
	ds_read_b64_tr_b16 v[134:135], v227 offset:54272
	ds_read_b64_tr_b16 v[136:137], v227 offset:54784
	v_exp_f32_e32 v208, v208
	v_exp_f32_e32 v209, v209
	v_cvt_pk_bf16_f32 v112, v206, v207
	s_waitcnt lgkmcnt(10)
	v_mfma_f32_32x32x16_bf16 v[50:65], v[98:101], v[114:117], v[50:65]
	ds_read_b64_tr_b16 v[138:139], v227 offset:55296
	ds_read_b64_tr_b16 v[140:141], v227 offset:55808
	v_cvt_pk_bf16_f32 v113, v208, v209
	v_pk_add_f32 v[82:83], v[162:163], v[146:147]
	v_pk_add_f32 v[84:85], v[194:195], v[178:179]
	s_waitcnt lgkmcnt(10)
	v_mfma_f32_32x32x16_bf16 v[50:65], v[102:105], v[118:121], v[50:65]
	ds_read_b64_tr_b16 v[142:143], v227 offset:56320
	ds_read_b64_tr_b16 v[144:145], v227 offset:56832
	s_waitcnt lgkmcnt(10)
	v_mfma_f32_32x32x16_bf16 v[50:65], v[106:109], v[122:125], v[50:65]
	ds_read_b64_tr_b16 v[114:115], v227 offset:57344
	ds_read_b64_tr_b16 v[116:117], v227 offset:57856
	v_pk_add_f32 v[86:87], v[164:165], v[148:149]
	v_pk_add_f32 v[88:89], v[196:197], v[180:181]
	s_waitcnt lgkmcnt(10)
	v_mfma_f32_32x32x16_bf16 v[50:65], v[110:113], v[126:129], v[50:65]
	ds_read_b64_tr_b16 v[118:119], v227 offset:58368
	ds_read_b64_tr_b16 v[120:121], v227 offset:58880
	v_pk_add_f32 v[82:83], v[86:87], v[82:83]
	v_pk_add_f32 v[84:85], v[88:89], v[84:85]
	s_waitcnt lgkmcnt(10)
	v_mfma_f32_32x32x16_bf16 v[34:49], v[98:101], v[130:133], v[34:49]
	ds_read_b64_tr_b16 v[122:123], v227 offset:59392
	ds_read_b64_tr_b16 v[124:125], v227 offset:59904
	v_pk_add_f32 v[86:87], v[166:167], v[150:151]
	v_pk_add_f32 v[88:89], v[198:199], v[182:183]
	s_waitcnt lgkmcnt(10)
	v_mfma_f32_32x32x16_bf16 v[34:49], v[102:105], v[134:137], v[34:49]
	ds_read_b64_tr_b16 v[126:127], v227 offset:60416
	ds_read_b64_tr_b16 v[128:129], v227 offset:60928
	v_pk_add_f32 v[82:83], v[86:87], v[82:83]
	v_pk_add_f32 v[84:85], v[88:89], v[84:85]
	s_waitcnt lgkmcnt(10)
	v_mfma_f32_32x32x16_bf16 v[34:49], v[106:109], v[138:141], v[34:49]
	ds_read_b64_tr_b16 v[130:131], v227 offset:61440
	ds_read_b64_tr_b16 v[132:133], v227 offset:61952
	v_pk_add_f32 v[86:87], v[168:169], v[152:153]
	v_pk_add_f32 v[88:89], v[200:201], v[184:185]
	s_waitcnt lgkmcnt(10)
	v_mfma_f32_32x32x16_bf16 v[34:49], v[110:113], v[142:145], v[34:49]
	ds_read_b64_tr_b16 v[134:135], v227 offset:62464
	ds_read_b64_tr_b16 v[136:137], v227 offset:62976
	v_pk_add_f32 v[82:83], v[86:87], v[82:83]
	v_pk_add_f32 v[84:85], v[88:89], v[84:85]
	s_waitcnt lgkmcnt(10)
	v_mfma_f32_32x32x16_bf16 v[18:33], v[98:101], v[114:117], v[18:33]
	ds_read_b64_tr_b16 v[138:139], v227 offset:63488
	ds_read_b64_tr_b16 v[140:141], v227 offset:64000
	v_pk_add_f32 v[86:87], v[170:171], v[154:155]
	v_pk_add_f32 v[88:89], v[202:203], v[186:187]
	s_waitcnt lgkmcnt(10)
	v_mfma_f32_32x32x16_bf16 v[18:33], v[102:105], v[118:121], v[18:33]
	ds_read_b64_tr_b16 v[142:143], v227 offset:64512
	ds_read_b64_tr_b16 v[144:145], v227 offset:65024
	v_pk_add_f32 v[82:83], v[86:87], v[82:83]
	v_pk_add_f32 v[84:85], v[88:89], v[84:85]
	s_waitcnt lgkmcnt(10)
	v_mfma_f32_32x32x16_bf16 v[18:33], v[106:109], v[122:125], v[18:33]
	v_pk_add_f32 v[86:87], v[172:173], v[156:157]
	v_pk_add_f32 v[88:89], v[204:205], v[188:189]
	s_waitcnt lgkmcnt(8)
	v_mfma_f32_32x32x16_bf16 v[18:33], v[110:113], v[126:129], v[18:33]
	v_pk_add_f32 v[82:83], v[86:87], v[82:83]
	v_pk_add_f32 v[84:85], v[88:89], v[84:85]
	s_waitcnt lgkmcnt(6)
	v_mfma_f32_32x32x16_bf16 v[2:17], v[98:101], v[130:133], v[2:17]
	v_pk_add_f32 v[86:87], v[174:175], v[158:159]
	v_pk_add_f32 v[88:89], v[206:207], v[190:191]
	s_waitcnt lgkmcnt(4)
	v_mfma_f32_32x32x16_bf16 v[2:17], v[102:105], v[134:137], v[2:17]
	v_pk_add_f32 v[82:83], v[86:87], v[82:83]
	v_pk_add_f32 v[84:85], v[88:89], v[84:85]
	s_waitcnt lgkmcnt(2)
	v_mfma_f32_32x32x16_bf16 v[2:17], v[106:109], v[138:141], v[2:17]
	v_pk_add_f32 v[86:87], v[176:177], v[160:161]
	v_pk_add_f32 v[88:89], v[208:209], v[192:193]
	s_waitcnt lgkmcnt(0)
	v_mfma_f32_32x32x16_bf16 v[2:17], v[110:113], v[142:145], v[2:17]
	v_pk_add_f32 v[82:83], v[86:87], v[82:83]
	v_pk_add_f32 v[84:85], v[88:89], v[84:85]
	v_pk_add_f32 v[82:83], v[82:83], v[84:85]
	s_nop 0
	v_add_f32_e32 v226, v82, v83
	v_add_f32_e32 v0, v237, v226
	s_branch .Lattn_pv_done
.Lattn_pv_nodma:
	v_lshl_add_u32 v227, s36, 15, v230
	ds_read_b64_tr_b16 v[114:115], v227 offset:32768
	ds_read_b64_tr_b16 v[116:117], v227 offset:33280
	ds_read_b64_tr_b16 v[118:119], v227 offset:33792
	ds_read_b64_tr_b16 v[120:121], v227 offset:34304
	ds_read_b64_tr_b16 v[122:123], v227 offset:34816
	ds_read_b64_tr_b16 v[124:125], v227 offset:35328
	ds_read_b64_tr_b16 v[126:127], v227 offset:35840
	ds_read_b64_tr_b16 v[128:129], v227 offset:36352
	ds_read_b64_tr_b16 v[130:131], v227 offset:36864
	ds_read_b64_tr_b16 v[132:133], v227 offset:37376
	ds_read_b64_tr_b16 v[134:135], v227 offset:37888
	ds_read_b64_tr_b16 v[136:137], v227 offset:38400
	v_exp_f32_e32 v146, v146
	v_exp_f32_e32 v147, v147
	v_exp_f32_e32 v162, v162
	v_exp_f32_e32 v163, v163
	v_exp_f32_e32 v148, v148
	v_exp_f32_e32 v149, v149
	v_exp_f32_e32 v164, v164
	v_exp_f32_e32 v165, v165
	v_cvt_pk_bf16_f32 v82, v146, v147
	v_cvt_pk_bf16_f32 v90, v162, v163
	v_exp_f32_e32 v150, v150
	v_exp_f32_e32 v151, v151
	v_exp_f32_e32 v166, v166
	v_exp_f32_e32 v167, v167
	v_cvt_pk_bf16_f32 v83, v148, v149
	v_cvt_pk_bf16_f32 v91, v164, v165
	v_exp_f32_e32 v152, v152
	v_exp_f32_e32 v153, v153
	v_exp_f32_e32 v168, v168
	v_exp_f32_e32 v169, v169
	v_cvt_pk_bf16_f32 v84, v150, v151
	v_cvt_pk_bf16_f32 v92, v166, v167
	v_exp_f32_e32 v154, v154
	v_exp_f32_e32 v155, v155
	v_exp_f32_e32 v170, v170
	v_exp_f32_e32 v171, v171
	v_cvt_pk_bf16_f32 v85, v152, v153
	v_cvt_pk_bf16_f32 v93, v168, v169
	v_exp_f32_e32 v156, v156
	v_exp_f32_e32 v157, v157
	v_exp_f32_e32 v172, v172
	v_exp_f32_e32 v173, v173
	v_cvt_pk_bf16_f32 v86, v154, v155
	v_cvt_pk_bf16_f32 v94, v170, v171
	v_exp_f32_e32 v158, v158
	v_exp_f32_e32 v159, v159
	v_exp_f32_e32 v174, v174
	v_exp_f32_e32 v175, v175
	v_cvt_pk_bf16_f32 v87, v156, v157
	v_cvt_pk_bf16_f32 v95, v172, v173
	v_exp_f32_e32 v160, v160
	v_exp_f32_e32 v161, v161
	v_exp_f32_e32 v176, v176
	v_exp_f32_e32 v177, v177
	v_cvt_pk_bf16_f32 v88, v158, v159
	v_cvt_pk_bf16_f32 v96, v174, v175
	s_nop 0
	v_cvt_pk_bf16_f32 v89, v160, v161
	v_cvt_pk_bf16_f32 v97, v176, v177
	s_waitcnt lgkmcnt(10)
	v_mfma_f32_32x32x16_bf16 v[50:65], v[82:85], v[114:117], v[50:65]
	ds_read_b64_tr_b16 v[138:139], v227 offset:38912
	ds_read_b64_tr_b16 v[140:141], v227 offset:39424
	v_exp_f32_e32 v178, v178
	v_exp_f32_e32 v179, v179
	s_waitcnt lgkmcnt(10)
	v_mfma_f32_32x32x16_bf16 v[50:65], v[86:89], v[118:121], v[50:65]
	ds_read_b64_tr_b16 v[142:143], v227 offset:39936
	ds_read_b64_tr_b16 v[144:145], v227 offset:40448
	v_exp_f32_e32 v180, v180
	v_exp_f32_e32 v181, v181
	v_cvt_pk_bf16_f32 v98, v178, v179
	s_waitcnt lgkmcnt(10)
	v_mfma_f32_32x32x16_bf16 v[50:65], v[90:93], v[122:125], v[50:65]
	ds_read_b64_tr_b16 v[114:115], v227 offset:40960
	ds_read_b64_tr_b16 v[116:117], v227 offset:41472
	v_exp_f32_e32 v182, v182
	v_exp_f32_e32 v183, v183
	v_cvt_pk_bf16_f32 v99, v180, v181
	s_waitcnt lgkmcnt(10)
	v_mfma_f32_32x32x16_bf16 v[50:65], v[94:97], v[126:129], v[50:65]
	ds_read_b64_tr_b16 v[118:119], v227 offset:41984
	ds_read_b64_tr_b16 v[120:121], v227 offset:42496
	v_exp_f32_e32 v184, v184
	v_exp_f32_e32 v185, v185
	v_cvt_pk_bf16_f32 v100, v182, v183
	s_waitcnt lgkmcnt(10)
	v_mfma_f32_32x32x16_bf16 v[34:49], v[82:85], v[130:133], v[34:49]
	ds_read_b64_tr_b16 v[122:123], v227 offset:43008
	ds_read_b64_tr_b16 v[124:125], v227 offset:43520
	v_exp_f32_e32 v186, v186
	v_exp_f32_e32 v187, v187
	v_cvt_pk_bf16_f32 v101, v184, v185
	s_waitcnt lgkmcnt(10)
	v_mfma_f32_32x32x16_bf16 v[34:49], v[86:89], v[134:137], v[34:49]
	ds_read_b64_tr_b16 v[126:127], v227 offset:44032
	ds_read_b64_tr_b16 v[128:129], v227 offset:44544
	v_exp_f32_e32 v188, v188
	v_exp_f32_e32 v189, v189
	v_cvt_pk_bf16_f32 v102, v186, v187
	s_waitcnt lgkmcnt(10)
	v_mfma_f32_32x32x16_bf16 v[34:49], v[90:93], v[138:141], v[34:49]
	ds_read_b64_tr_b16 v[130:131], v227 offset:45056
	ds_read_b64_tr_b16 v[132:133], v227 offset:45568
	v_exp_f32_e32 v190, v190
	v_exp_f32_e32 v191, v191
	v_cvt_pk_bf16_f32 v103, v188, v189
	s_waitcnt lgkmcnt(10)
	v_mfma_f32_32x32x16_bf16 v[34:49], v[94:97], v[142:145], v[34:49]
	ds_read_b64_tr_b16 v[134:135], v227 offset:46080
	ds_read_b64_tr_b16 v[136:137], v227 offset:46592
	v_exp_f32_e32 v192, v192
	v_exp_f32_e32 v193, v193
	v_cvt_pk_bf16_f32 v104, v190, v191
	s_waitcnt lgkmcnt(10)
	v_mfma_f32_32x32x16_bf16 v[18:33], v[82:85], v[114:117], v[18:33]
	ds_read_b64_tr_b16 v[138:139], v227 offset:47104
	ds_read_b64_tr_b16 v[140:141], v227 offset:47616
	v_exp_f32_e32 v194, v194
	v_exp_f32_e32 v195, v195
	v_cvt_pk_bf16_f32 v105, v192, v193
	s_waitcnt lgkmcnt(10)
	v_mfma_f32_32x32x16_bf16 v[18:33], v[86:89], v[118:121], v[18:33]
	ds_read_b64_tr_b16 v[142:143], v227 offset:48128
	ds_read_b64_tr_b16 v[144:145], v227 offset:48640
	v_exp_f32_e32 v196, v196
	v_exp_f32_e32 v197, v197
	v_cvt_pk_bf16_f32 v106, v194, v195
	s_waitcnt lgkmcnt(10)
	v_mfma_f32_32x32x16_bf16 v[18:33], v[90:93], v[122:125], v[18:33]
	ds_read_b64_tr_b16 v[114:115], v227 offset:49152
	ds_read_b64_tr_b16 v[116:117], v227 offset:49664
	v_exp_f32_e32 v198, v198
	v_exp_f32_e32 v199, v199
	v_cvt_pk_bf16_f32 v107, v196, v197
	s_waitcnt lgkmcnt(10)
	v_mfma_f32_32x32x16_bf16 v[18:33], v[94:97], v[126:129], v[18:33]
	ds_read_b64_tr_b16 v[118:119], v227 offset:50176
	ds_read_b64_tr_b16 v[120:121], v227 offset:50688
	v_exp_f32_e32 v200, v200
	v_exp_f32_e32 v201, v201
	v_cvt_pk_bf16_f32 v108, v198, v199
	s_waitcnt lgkmcnt(10)
	v_mfma_f32_32x32x16_bf16 v[2:17], v[82:85], v[130:133], v[2:17]
	ds_read_b64_tr_b16 v[122:123], v227 offset:51200
	ds_read_b64_tr_b16 v[124:125], v227 offset:51712
	v_exp_f32_e32 v202, v202
	v_exp_f32_e32 v203, v203
	v_cvt_pk_bf16_f32 v109, v200, v201
	s_waitcnt lgkmcnt(10)
	v_mfma_f32_32x32x16_bf16 v[2:17], v[86:89], v[134:137], v[2:17]
	ds_read_b64_tr_b16 v[126:127], v227 offset:52224
	ds_read_b64_tr_b16 v[128:129], v227 offset:52736
	v_exp_f32_e32 v204, v204
	v_exp_f32_e32 v205, v205
	v_cvt_pk_bf16_f32 v110, v202, v203
	s_waitcnt lgkmcnt(10)
	v_mfma_f32_32x32x16_bf16 v[2:17], v[90:93], v[138:141], v[2:17]
	ds_read_b64_tr_b16 v[130:131], v227 offset:53248
	ds_read_b64_tr_b16 v[132:133], v227 offset:53760
	v_exp_f32_e32 v206, v206
	v_exp_f32_e32 v207, v207
	v_cvt_pk_bf16_f32 v111, v204, v205
	s_waitcnt lgkmcnt(10)
	v_mfma_f32_32x32x16_bf16 v[2:17], v[94:97], v[142:145], v[2:17]
	ds_read_b64_tr_b16 v[134:135], v227 offset:54272
	ds_read_b64_tr_b16 v[136:137], v227 offset:54784
	v_exp_f32_e32 v208, v208
	v_exp_f32_e32 v209, v209
	v_cvt_pk_bf16_f32 v112, v206, v207
	s_waitcnt lgkmcnt(10)
	v_mfma_f32_32x32x16_bf16 v[50:65], v[98:101], v[114:117], v[50:65]
	ds_read_b64_tr_b16 v[138:139], v227 offset:55296
	ds_read_b64_tr_b16 v[140:141], v227 offset:55808
	v_cvt_pk_bf16_f32 v113, v208, v209
	v_pk_add_f32 v[82:83], v[162:163], v[146:147]
	v_pk_add_f32 v[84:85], v[194:195], v[178:179]
	s_waitcnt lgkmcnt(10)
	v_mfma_f32_32x32x16_bf16 v[50:65], v[102:105], v[118:121], v[50:65]
	ds_read_b64_tr_b16 v[142:143], v227 offset:56320
	ds_read_b64_tr_b16 v[144:145], v227 offset:56832
	s_waitcnt lgkmcnt(10)
	v_mfma_f32_32x32x16_bf16 v[50:65], v[106:109], v[122:125], v[50:65]
	ds_read_b64_tr_b16 v[114:115], v227 offset:57344
	ds_read_b64_tr_b16 v[116:117], v227 offset:57856
	v_pk_add_f32 v[86:87], v[164:165], v[148:149]
	v_pk_add_f32 v[88:89], v[196:197], v[180:181]
	s_waitcnt lgkmcnt(10)
	v_mfma_f32_32x32x16_bf16 v[50:65], v[110:113], v[126:129], v[50:65]
	ds_read_b64_tr_b16 v[118:119], v227 offset:58368
	ds_read_b64_tr_b16 v[120:121], v227 offset:58880
	v_pk_add_f32 v[82:83], v[86:87], v[82:83]
	v_pk_add_f32 v[84:85], v[88:89], v[84:85]
	s_waitcnt lgkmcnt(10)
	v_mfma_f32_32x32x16_bf16 v[34:49], v[98:101], v[130:133], v[34:49]
	ds_read_b64_tr_b16 v[122:123], v227 offset:59392
	ds_read_b64_tr_b16 v[124:125], v227 offset:59904
	v_pk_add_f32 v[86:87], v[166:167], v[150:151]
	v_pk_add_f32 v[88:89], v[198:199], v[182:183]
	s_waitcnt lgkmcnt(10)
	v_mfma_f32_32x32x16_bf16 v[34:49], v[102:105], v[134:137], v[34:49]
	ds_read_b64_tr_b16 v[126:127], v227 offset:60416
	ds_read_b64_tr_b16 v[128:129], v227 offset:60928
	v_pk_add_f32 v[82:83], v[86:87], v[82:83]
	v_pk_add_f32 v[84:85], v[88:89], v[84:85]
	s_waitcnt lgkmcnt(10)
	v_mfma_f32_32x32x16_bf16 v[34:49], v[106:109], v[138:141], v[34:49]
	ds_read_b64_tr_b16 v[130:131], v227 offset:61440
	ds_read_b64_tr_b16 v[132:133], v227 offset:61952
	v_pk_add_f32 v[86:87], v[168:169], v[152:153]
	v_pk_add_f32 v[88:89], v[200:201], v[184:185]
	s_waitcnt lgkmcnt(10)
	v_mfma_f32_32x32x16_bf16 v[34:49], v[110:113], v[142:145], v[34:49]
	ds_read_b64_tr_b16 v[134:135], v227 offset:62464
	ds_read_b64_tr_b16 v[136:137], v227 offset:62976
	v_pk_add_f32 v[82:83], v[86:87], v[82:83]
	v_pk_add_f32 v[84:85], v[88:89], v[84:85]
	s_waitcnt lgkmcnt(10)
	v_mfma_f32_32x32x16_bf16 v[18:33], v[98:101], v[114:117], v[18:33]
	ds_read_b64_tr_b16 v[138:139], v227 offset:63488
	ds_read_b64_tr_b16 v[140:141], v227 offset:64000
	v_pk_add_f32 v[86:87], v[170:171], v[154:155]
	v_pk_add_f32 v[88:89], v[202:203], v[186:187]
	s_waitcnt lgkmcnt(10)
	v_mfma_f32_32x32x16_bf16 v[18:33], v[102:105], v[118:121], v[18:33]
	ds_read_b64_tr_b16 v[142:143], v227 offset:64512
	ds_read_b64_tr_b16 v[144:145], v227 offset:65024
	v_pk_add_f32 v[82:83], v[86:87], v[82:83]
	v_pk_add_f32 v[84:85], v[88:89], v[84:85]
	s_waitcnt lgkmcnt(10)
	v_mfma_f32_32x32x16_bf16 v[18:33], v[106:109], v[122:125], v[18:33]
	v_pk_add_f32 v[86:87], v[172:173], v[156:157]
	v_pk_add_f32 v[88:89], v[204:205], v[188:189]
	s_waitcnt lgkmcnt(8)
	v_mfma_f32_32x32x16_bf16 v[18:33], v[110:113], v[126:129], v[18:33]
	v_pk_add_f32 v[82:83], v[86:87], v[82:83]
	v_pk_add_f32 v[84:85], v[88:89], v[84:85]
	s_waitcnt lgkmcnt(6)
	v_mfma_f32_32x32x16_bf16 v[2:17], v[98:101], v[130:133], v[2:17]
	v_pk_add_f32 v[86:87], v[174:175], v[158:159]
	v_pk_add_f32 v[88:89], v[206:207], v[190:191]
	s_waitcnt lgkmcnt(4)
	v_mfma_f32_32x32x16_bf16 v[2:17], v[102:105], v[134:137], v[2:17]
	v_pk_add_f32 v[82:83], v[86:87], v[82:83]
	v_pk_add_f32 v[84:85], v[88:89], v[84:85]
	s_waitcnt lgkmcnt(2)
	v_mfma_f32_32x32x16_bf16 v[2:17], v[106:109], v[138:141], v[2:17]
	v_pk_add_f32 v[86:87], v[176:177], v[160:161]
	v_pk_add_f32 v[88:89], v[208:209], v[192:193]
	s_waitcnt lgkmcnt(0)
	v_mfma_f32_32x32x16_bf16 v[2:17], v[110:113], v[142:145], v[2:17]
	v_pk_add_f32 v[82:83], v[86:87], v[82:83]
	v_pk_add_f32 v[84:85], v[88:89], v[84:85]
	v_pk_add_f32 v[82:83], v[82:83], v[84:85]
	s_nop 0
	v_add_f32_e32 v226, v82, v83
	v_add_f32_e32 v0, v237, v226
